# gate-column GEMM jobs epilogue rewritten (bias once, no per-block waits) on top of lora+fused norms
# baseline (speedup 1.0000x reference)
; __device__ __forceinline__ float sigmoidf_(float x) { return __builtin_amdgcn_rcpf(1.f + __expf(-x)); }
;     __device__ __forceinline__ void emit(int row, int pn, int col0, float* v) const {
;     ...
;             else { const int cg_ = col0 - 3840; const f32x4 b0 = ldg<f32x4>(f0 + cg_), b1 = ldg<f32x4>(f0 + cg_ + 4);
;                 v[0] = sigmoidf_(v[0] + b0.x); v[1] = sigmoidf_(v[1] + b0.y); v[2] = sigmoidf_(v[2] + b0.z); v[3] = sigmoidf_(v[3] + b0.w);
;                 v[4] = sigmoidf_(v[4] + b1.x); v[5] = sigmoidf_(v[5] + b1.y); v[6] = sigmoidf_(v[6] + b1.z); v[7] = sigmoidf_(v[7] + b1.w);
;                 store8((bf16_t*)(ws + WS_GATE) + (size_t)row * GT_COLS + cg_, v); }
;     __device__ __forceinline__ void operator()(const f32x4 (&acc)[2][2][4][2], const pg8::Unit& u, int wr, int wc, int fr, int fq) const {
;         const int row0 = u.pm * 256 + wr * 64 + fr, colb = u.pn * 256 + wc * 32 + 8 * fq;
; #pragma unroll
;         for (int ai = 0; ai < 2; ++ai)
; #pragma unroll
;             for (int m = 0; m < 4; ++m)
; #pragma unroll
;                 for (int bj = 0; bj < 2; ++bj) {
;                     float v[8]; const f32x4 v0 = acc[ai][bj][m][0], v1 = acc[ai][bj][m][1];
;                     v[0] = v0.x; v[1] = v0.y; v[2] = v0.z; v[3] = v0.w; v[4] = v1.x; v[5] = v1.y; v[6] = v1.z; v[7] = v1.w;
;                     emit(row0 + ai * 128 + m * 16, u.pn, colb + bj * 128, v);
;                 }
;     }
.Lgt_epi:
	v_lshl_or_b32 v163, s2, 8, v161
	v_add_u32_e32 v0, 0xfffff100, v163
	v_lshlrev_b32_e32 v226, 1, v0
	v_mov_b32_e32 v227, 0
	v_lshlrev_b32_e32 v0, 2, v0
	global_load_dwordx4 v[210:213], v0, s[6:7]
	global_load_dwordx4 v[214:217], v0, s[6:7] offset:16
	global_load_dwordx4 v[218:221], v0, s[6:7] offset:512
	global_load_dwordx4 v[222:225], v0, s[6:7] offset:528
	s_waitcnt vmcnt(0)
	v_pk_add_f32 v[126:127], v[126:127], v[210:211]
	v_pk_add_f32 v[128:129], v[128:129], v[212:213]
	v_pk_add_f32 v[122:123], v[122:123], v[214:215]
	v_pk_add_f32 v[124:125], v[124:125], v[216:217]
	v_mul_f32_e32 v126, 0xbfb8aa3b, v126
	v_mul_f32_e32 v127, 0xbfb8aa3b, v127
	v_mul_f32_e32 v128, 0xbfb8aa3b, v128
	v_mul_f32_e32 v129, 0xbfb8aa3b, v129
	v_mul_f32_e32 v122, 0xbfb8aa3b, v122
	v_mul_f32_e32 v123, 0xbfb8aa3b, v123
	v_mul_f32_e32 v124, 0xbfb8aa3b, v124
	v_mul_f32_e32 v125, 0xbfb8aa3b, v125
	v_exp_f32_e32 v126, v126
	v_exp_f32_e32 v127, v127
	v_exp_f32_e32 v128, v128
	v_exp_f32_e32 v129, v129
	v_exp_f32_e32 v122, v122
	v_exp_f32_e32 v123, v123
	v_exp_f32_e32 v124, v124
	v_exp_f32_e32 v125, v125
	v_add_f32_e32 v126, 1.0, v126
	v_add_f32_e32 v127, 1.0, v127
	v_add_f32_e32 v128, 1.0, v128
	v_add_f32_e32 v129, 1.0, v129
	v_add_f32_e32 v122, 1.0, v122
	v_add_f32_e32 v123, 1.0, v123
	v_add_f32_e32 v124, 1.0, v124
	v_add_f32_e32 v125, 1.0, v125
	v_rcp_f32_e32 v126, v126
	v_rcp_f32_e32 v127, v127
	v_rcp_f32_e32 v128, v128
	v_rcp_f32_e32 v129, v129
	v_rcp_f32_e32 v122, v122
	v_rcp_f32_e32 v123, v123
	v_rcp_f32_e32 v124, v124
	v_rcp_f32_e32 v125, v125
	s_nop 0
	v_cvt_pk_bf16_f32 v228, v126, v127
	v_cvt_pk_bf16_f32 v229, v128, v129
	v_cvt_pk_bf16_f32 v230, v122, v123
	v_cvt_pk_bf16_f32 v231, v124, v125
	v_lshl_add_u64 v[236:237], v[138:139], 0, v[226:227]
	global_store_dwordx4 v[236:237], v[228:231], off
	v_pk_add_f32 v[118:119], v[118:119], v[218:219]
	v_pk_add_f32 v[120:121], v[120:121], v[220:221]
	v_pk_add_f32 v[114:115], v[114:115], v[222:223]
	v_pk_add_f32 v[116:117], v[116:117], v[224:225]
	v_mul_f32_e32 v118, 0xbfb8aa3b, v118
	v_mul_f32_e32 v119, 0xbfb8aa3b, v119
	v_mul_f32_e32 v120, 0xbfb8aa3b, v120
	v_mul_f32_e32 v121, 0xbfb8aa3b, v121
	v_mul_f32_e32 v114, 0xbfb8aa3b, v114
	v_mul_f32_e32 v115, 0xbfb8aa3b, v115
	v_mul_f32_e32 v116, 0xbfb8aa3b, v116
	v_mul_f32_e32 v117, 0xbfb8aa3b, v117
	v_exp_f32_e32 v118, v118
	v_exp_f32_e32 v119, v119
	v_exp_f32_e32 v120, v120
	v_exp_f32_e32 v121, v121
	v_exp_f32_e32 v114, v114
	v_exp_f32_e32 v115, v115
	v_exp_f32_e32 v116, v116
	v_exp_f32_e32 v117, v117
	v_add_f32_e32 v118, 1.0, v118
	v_add_f32_e32 v119, 1.0, v119
	v_add_f32_e32 v120, 1.0, v120
	v_add_f32_e32 v121, 1.0, v121
	v_add_f32_e32 v114, 1.0, v114
	v_add_f32_e32 v115, 1.0, v115
	v_add_f32_e32 v116, 1.0, v116
	v_add_f32_e32 v117, 1.0, v117
	v_rcp_f32_e32 v118, v118
	v_rcp_f32_e32 v119, v119
	v_rcp_f32_e32 v120, v120
	v_rcp_f32_e32 v121, v121
	v_rcp_f32_e32 v114, v114
	v_rcp_f32_e32 v115, v115
	v_rcp_f32_e32 v116, v116
	v_rcp_f32_e32 v117, v117
	s_nop 0
	v_cvt_pk_bf16_f32 v232, v118, v119
	v_cvt_pk_bf16_f32 v233, v120, v121
	v_cvt_pk_bf16_f32 v234, v114, v115
	v_cvt_pk_bf16_f32 v235, v116, v117
	v_lshl_add_u64 v[238:239], v[138:139], 0, v[226:227]
	global_store_dwordx4 v[238:239], v[232:235], off offset:256
	v_pk_add_f32 v[110:111], v[110:111], v[210:211]
	v_pk_add_f32 v[112:113], v[112:113], v[212:213]
	v_pk_add_f32 v[106:107], v[106:107], v[214:215]
	v_pk_add_f32 v[108:109], v[108:109], v[216:217]
	v_mul_f32_e32 v110, 0xbfb8aa3b, v110
	v_mul_f32_e32 v111, 0xbfb8aa3b, v111
	v_mul_f32_e32 v112, 0xbfb8aa3b, v112
	v_mul_f32_e32 v113, 0xbfb8aa3b, v113
	v_mul_f32_e32 v106, 0xbfb8aa3b, v106
	v_mul_f32_e32 v107, 0xbfb8aa3b, v107
	v_mul_f32_e32 v108, 0xbfb8aa3b, v108
	v_mul_f32_e32 v109, 0xbfb8aa3b, v109
	v_exp_f32_e32 v110, v110
	v_exp_f32_e32 v111, v111
	v_exp_f32_e32 v112, v112
	v_exp_f32_e32 v113, v113
	v_exp_f32_e32 v106, v106
	v_exp_f32_e32 v107, v107
	v_exp_f32_e32 v108, v108
	v_exp_f32_e32 v109, v109
	v_add_f32_e32 v110, 1.0, v110
	v_add_f32_e32 v111, 1.0, v111
	v_add_f32_e32 v112, 1.0, v112
	v_add_f32_e32 v113, 1.0, v113
	v_add_f32_e32 v106, 1.0, v106
	v_add_f32_e32 v107, 1.0, v107
	v_add_f32_e32 v108, 1.0, v108
	v_add_f32_e32 v109, 1.0, v109
	v_rcp_f32_e32 v110, v110
	v_rcp_f32_e32 v111, v111
	v_rcp_f32_e32 v112, v112
	v_rcp_f32_e32 v113, v113
	v_rcp_f32_e32 v106, v106
	v_rcp_f32_e32 v107, v107
	v_rcp_f32_e32 v108, v108
	v_rcp_f32_e32 v109, v109
	s_nop 0
	v_cvt_pk_bf16_f32 v228, v110, v111
	v_cvt_pk_bf16_f32 v229, v112, v113
	v_cvt_pk_bf16_f32 v230, v106, v107
	v_cvt_pk_bf16_f32 v231, v108, v109
	v_lshl_add_u64 v[236:237], v[140:141], 0, v[226:227]
	global_store_dwordx4 v[236:237], v[228:231], off
	v_pk_add_f32 v[102:103], v[102:103], v[218:219]
	v_pk_add_f32 v[104:105], v[104:105], v[220:221]
	v_pk_add_f32 v[98:99], v[98:99], v[222:223]
	v_pk_add_f32 v[100:101], v[100:101], v[224:225]
	v_mul_f32_e32 v102, 0xbfb8aa3b, v102
	v_mul_f32_e32 v103, 0xbfb8aa3b, v103
	v_mul_f32_e32 v104, 0xbfb8aa3b, v104
	v_mul_f32_e32 v105, 0xbfb8aa3b, v105
	v_mul_f32_e32 v98, 0xbfb8aa3b, v98
	v_mul_f32_e32 v99, 0xbfb8aa3b, v99
	v_mul_f32_e32 v100, 0xbfb8aa3b, v100
	v_mul_f32_e32 v101, 0xbfb8aa3b, v101
	v_exp_f32_e32 v102, v102
	v_exp_f32_e32 v103, v103
	v_exp_f32_e32 v104, v104
	v_exp_f32_e32 v105, v105
	v_exp_f32_e32 v98, v98
	v_exp_f32_e32 v99, v99
	v_exp_f32_e32 v100, v100
	v_exp_f32_e32 v101, v101
	v_add_f32_e32 v102, 1.0, v102
	v_add_f32_e32 v103, 1.0, v103
	v_add_f32_e32 v104, 1.0, v104
	v_add_f32_e32 v105, 1.0, v105
	v_add_f32_e32 v98, 1.0, v98
	v_add_f32_e32 v99, 1.0, v99
	v_add_f32_e32 v100, 1.0, v100
	v_add_f32_e32 v101, 1.0, v101
	v_rcp_f32_e32 v102, v102
; __device__ __forceinline__ float sigmoidf_(float x) { return __builtin_amdgcn_rcpf(1.f + __expf(-x)); }
;     __device__ __forceinline__ void emit(int row, int pn, int col0, float* v) const {
;     ...
;             else { const int cg_ = col0 - 3840; const f32x4 b0 = ldg<f32x4>(f0 + cg_), b1 = ldg<f32x4>(f0 + cg_ + 4);
;                 v[0] = sigmoidf_(v[0] + b0.x); v[1] = sigmoidf_(v[1] + b0.y); v[2] = sigmoidf_(v[2] + b0.z); v[3] = sigmoidf_(v[3] + b0.w);
;                 v[4] = sigmoidf_(v[4] + b1.x); v[5] = sigmoidf_(v[5] + b1.y); v[6] = sigmoidf_(v[6] + b1.z); v[7] = sigmoidf_(v[7] + b1.w);
;                 store8((bf16_t*)(ws + WS_GATE) + (size_t)row * GT_COLS + cg_, v); }
;     __device__ __forceinline__ void operator()(const f32x4 (&acc)[2][2][4][2], const pg8::Unit& u, int wr, int wc, int fr, int fq) const {
;         const int row0 = u.pm * 256 + wr * 64 + fr, colb = u.pn * 256 + wc * 32 + 8 * fq;
; #pragma unroll
;         for (int ai = 0; ai < 2; ++ai)
; #pragma unroll
;             for (int m = 0; m < 4; ++m)
; #pragma unroll
;                 for (int bj = 0; bj < 2; ++bj) {
;                     float v[8]; const f32x4 v0 = acc[ai][bj][m][0], v1 = acc[ai][bj][m][1];
;                     v[0] = v0.x; v[1] = v0.y; v[2] = v0.z; v[3] = v0.w; v[4] = v1.x; v[5] = v1.y; v[6] = v1.z; v[7] = v1.w;
;                     emit(row0 + ai * 128 + m * 16, u.pn, colb + bj * 128, v);
;                 }
;     }
	v_rcp_f32_e32 v103, v103
	v_rcp_f32_e32 v104, v104
	v_rcp_f32_e32 v105, v105
	v_rcp_f32_e32 v98, v98
	v_rcp_f32_e32 v99, v99
	v_rcp_f32_e32 v100, v100
	v_rcp_f32_e32 v101, v101
	s_nop 0
	v_cvt_pk_bf16_f32 v232, v102, v103
	v_cvt_pk_bf16_f32 v233, v104, v105
	v_cvt_pk_bf16_f32 v234, v98, v99
	v_cvt_pk_bf16_f32 v235, v100, v101
	v_lshl_add_u64 v[238:239], v[140:141], 0, v[226:227]
	global_store_dwordx4 v[238:239], v[232:235], off offset:256
	v_pk_add_f32 v[94:95], v[94:95], v[210:211]
	v_pk_add_f32 v[96:97], v[96:97], v[212:213]
	v_pk_add_f32 v[90:91], v[90:91], v[214:215]
	v_pk_add_f32 v[92:93], v[92:93], v[216:217]
	v_mul_f32_e32 v94, 0xbfb8aa3b, v94
	v_mul_f32_e32 v95, 0xbfb8aa3b, v95
	v_mul_f32_e32 v96, 0xbfb8aa3b, v96
	v_mul_f32_e32 v97, 0xbfb8aa3b, v97
	v_mul_f32_e32 v90, 0xbfb8aa3b, v90
	v_mul_f32_e32 v91, 0xbfb8aa3b, v91
	v_mul_f32_e32 v92, 0xbfb8aa3b, v92
	v_mul_f32_e32 v93, 0xbfb8aa3b, v93
	v_exp_f32_e32 v94, v94
	v_exp_f32_e32 v95, v95
	v_exp_f32_e32 v96, v96
	v_exp_f32_e32 v97, v97
	v_exp_f32_e32 v90, v90
	v_exp_f32_e32 v91, v91
	v_exp_f32_e32 v92, v92
	v_exp_f32_e32 v93, v93
	v_add_f32_e32 v94, 1.0, v94
	v_add_f32_e32 v95, 1.0, v95
	v_add_f32_e32 v96, 1.0, v96
	v_add_f32_e32 v97, 1.0, v97
	v_add_f32_e32 v90, 1.0, v90
	v_add_f32_e32 v91, 1.0, v91
	v_add_f32_e32 v92, 1.0, v92
	v_add_f32_e32 v93, 1.0, v93
	v_rcp_f32_e32 v94, v94
	v_rcp_f32_e32 v95, v95
	v_rcp_f32_e32 v96, v96
	v_rcp_f32_e32 v97, v97
	v_rcp_f32_e32 v90, v90
	v_rcp_f32_e32 v91, v91
	v_rcp_f32_e32 v92, v92
	v_rcp_f32_e32 v93, v93
	s_nop 0
	v_cvt_pk_bf16_f32 v228, v94, v95
	v_cvt_pk_bf16_f32 v229, v96, v97
	v_cvt_pk_bf16_f32 v230, v90, v91
	v_cvt_pk_bf16_f32 v231, v92, v93
	v_lshl_add_u64 v[236:237], v[142:143], 0, v[226:227]
	global_store_dwordx4 v[236:237], v[228:231], off
	v_pk_add_f32 v[86:87], v[86:87], v[218:219]
	v_pk_add_f32 v[88:89], v[88:89], v[220:221]
	v_pk_add_f32 v[82:83], v[82:83], v[222:223]
	v_pk_add_f32 v[84:85], v[84:85], v[224:225]
	v_mul_f32_e32 v86, 0xbfb8aa3b, v86
	v_mul_f32_e32 v87, 0xbfb8aa3b, v87
	v_mul_f32_e32 v88, 0xbfb8aa3b, v88
	v_mul_f32_e32 v89, 0xbfb8aa3b, v89
	v_mul_f32_e32 v82, 0xbfb8aa3b, v82
	v_mul_f32_e32 v83, 0xbfb8aa3b, v83
	v_mul_f32_e32 v84, 0xbfb8aa3b, v84
	v_mul_f32_e32 v85, 0xbfb8aa3b, v85
	v_exp_f32_e32 v86, v86
	v_exp_f32_e32 v87, v87
	v_exp_f32_e32 v88, v88
	v_exp_f32_e32 v89, v89
	v_exp_f32_e32 v82, v82
	v_exp_f32_e32 v83, v83
	v_exp_f32_e32 v84, v84
	v_exp_f32_e32 v85, v85
	v_add_f32_e32 v86, 1.0, v86
	v_add_f32_e32 v87, 1.0, v87
	v_add_f32_e32 v88, 1.0, v88
	v_add_f32_e32 v89, 1.0, v89
	v_add_f32_e32 v82, 1.0, v82
	v_add_f32_e32 v83, 1.0, v83
	v_add_f32_e32 v84, 1.0, v84
	v_add_f32_e32 v85, 1.0, v85
	v_rcp_f32_e32 v86, v86
	v_rcp_f32_e32 v87, v87
	v_rcp_f32_e32 v88, v88
	v_rcp_f32_e32 v89, v89
	v_rcp_f32_e32 v82, v82
	v_rcp_f32_e32 v83, v83
	v_rcp_f32_e32 v84, v84
	v_rcp_f32_e32 v85, v85
	s_nop 0
	v_cvt_pk_bf16_f32 v232, v86, v87
	v_cvt_pk_bf16_f32 v233, v88, v89
	v_cvt_pk_bf16_f32 v234, v82, v83
	v_cvt_pk_bf16_f32 v235, v84, v85
	v_lshl_add_u64 v[238:239], v[142:143], 0, v[226:227]
	global_store_dwordx4 v[238:239], v[232:235], off offset:256
	v_pk_add_f32 v[78:79], v[78:79], v[210:211]
	v_pk_add_f32 v[80:81], v[80:81], v[212:213]
	v_pk_add_f32 v[74:75], v[74:75], v[214:215]
	v_pk_add_f32 v[76:77], v[76:77], v[216:217]
	v_mul_f32_e32 v78, 0xbfb8aa3b, v78
	v_mul_f32_e32 v79, 0xbfb8aa3b, v79
	v_mul_f32_e32 v80, 0xbfb8aa3b, v80
	v_mul_f32_e32 v81, 0xbfb8aa3b, v81
	v_mul_f32_e32 v74, 0xbfb8aa3b, v74
	v_mul_f32_e32 v75, 0xbfb8aa3b, v75
	v_mul_f32_e32 v76, 0xbfb8aa3b, v76
	v_mul_f32_e32 v77, 0xbfb8aa3b, v77
	v_exp_f32_e32 v78, v78
	v_exp_f32_e32 v79, v79
	v_exp_f32_e32 v80, v80
	v_exp_f32_e32 v81, v81
	v_exp_f32_e32 v74, v74
	v_exp_f32_e32 v75, v75
	v_exp_f32_e32 v76, v76
	v_exp_f32_e32 v77, v77
	v_add_f32_e32 v78, 1.0, v78
	v_add_f32_e32 v79, 1.0, v79
	v_add_f32_e32 v80, 1.0, v80
	v_add_f32_e32 v81, 1.0, v81
	v_add_f32_e32 v74, 1.0, v74
	v_add_f32_e32 v75, 1.0, v75
	v_add_f32_e32 v76, 1.0, v76
	v_add_f32_e32 v77, 1.0, v77
	v_rcp_f32_e32 v78, v78
	v_rcp_f32_e32 v79, v79
	v_rcp_f32_e32 v80, v80
	v_rcp_f32_e32 v81, v81
	v_rcp_f32_e32 v74, v74
	v_rcp_f32_e32 v75, v75
	v_rcp_f32_e32 v76, v76
	v_rcp_f32_e32 v77, v77
	s_nop 0
	v_cvt_pk_bf16_f32 v228, v78, v79
	v_cvt_pk_bf16_f32 v229, v80, v81
	v_cvt_pk_bf16_f32 v230, v74, v75
	v_cvt_pk_bf16_f32 v231, v76, v77
	v_lshl_add_u64 v[236:237], v[144:145], 0, v[226:227]
	global_store_dwordx4 v[236:237], v[228:231], off
	v_pk_add_f32 v[70:71], v[70:71], v[218:219]
	v_pk_add_f32 v[72:73], v[72:73], v[220:221]
	v_pk_add_f32 v[66:67], v[66:67], v[222:223]
	v_pk_add_f32 v[68:69], v[68:69], v[224:225]
	v_mul_f32_e32 v70, 0xbfb8aa3b, v70
	v_mul_f32_e32 v71, 0xbfb8aa3b, v71
	v_mul_f32_e32 v72, 0xbfb8aa3b, v72
	v_mul_f32_e32 v73, 0xbfb8aa3b, v73
	v_mul_f32_e32 v66, 0xbfb8aa3b, v66
	v_mul_f32_e32 v67, 0xbfb8aa3b, v67
	v_mul_f32_e32 v68, 0xbfb8aa3b, v68
	v_mul_f32_e32 v69, 0xbfb8aa3b, v69
	v_exp_f32_e32 v70, v70
	v_exp_f32_e32 v71, v71
	v_exp_f32_e32 v72, v72
	v_exp_f32_e32 v73, v73
	v_exp_f32_e32 v66, v66
	v_exp_f32_e32 v67, v67
	v_exp_f32_e32 v68, v68
	v_exp_f32_e32 v69, v69
	v_add_f32_e32 v70, 1.0, v70
	v_add_f32_e32 v71, 1.0, v71
	v_add_f32_e32 v72, 1.0, v72
	v_add_f32_e32 v73, 1.0, v73
	v_add_f32_e32 v66, 1.0, v66
	v_add_f32_e32 v67, 1.0, v67
	v_add_f32_e32 v68, 1.0, v68
	v_add_f32_e32 v69, 1.0, v69
	v_rcp_f32_e32 v70, v70
	v_rcp_f32_e32 v71, v71
	v_rcp_f32_e32 v72, v72
	v_rcp_f32_e32 v73, v73
	v_rcp_f32_e32 v66, v66
	v_rcp_f32_e32 v67, v67
	v_rcp_f32_e32 v68, v68
	v_rcp_f32_e32 v69, v69
	s_nop 0
	v_cvt_pk_bf16_f32 v232, v70, v71
	v_cvt_pk_bf16_f32 v233, v72, v73
	v_cvt_pk_bf16_f32 v234, v66, v67
; __device__ __forceinline__ float sigmoidf_(float x) { return __builtin_amdgcn_rcpf(1.f + __expf(-x)); }
;     __device__ __forceinline__ void emit(int row, int pn, int col0, float* v) const {
;     ...
;             else { const int cg_ = col0 - 3840; const f32x4 b0 = ldg<f32x4>(f0 + cg_), b1 = ldg<f32x4>(f0 + cg_ + 4);
;                 v[0] = sigmoidf_(v[0] + b0.x); v[1] = sigmoidf_(v[1] + b0.y); v[2] = sigmoidf_(v[2] + b0.z); v[3] = sigmoidf_(v[3] + b0.w);
;                 v[4] = sigmoidf_(v[4] + b1.x); v[5] = sigmoidf_(v[5] + b1.y); v[6] = sigmoidf_(v[6] + b1.z); v[7] = sigmoidf_(v[7] + b1.w);
;                 store8((bf16_t*)(ws + WS_GATE) + (size_t)row * GT_COLS + cg_, v); }
;     __device__ __forceinline__ void operator()(const f32x4 (&acc)[2][2][4][2], const pg8::Unit& u, int wr, int wc, int fr, int fq) const {
;         const int row0 = u.pm * 256 + wr * 64 + fr, colb = u.pn * 256 + wc * 32 + 8 * fq;
; #pragma unroll
;         for (int ai = 0; ai < 2; ++ai)
; #pragma unroll
;             for (int m = 0; m < 4; ++m)
; #pragma unroll
;                 for (int bj = 0; bj < 2; ++bj) {
;                     float v[8]; const f32x4 v0 = acc[ai][bj][m][0], v1 = acc[ai][bj][m][1];
;                     v[0] = v0.x; v[1] = v0.y; v[2] = v0.z; v[3] = v0.w; v[4] = v1.x; v[5] = v1.y; v[6] = v1.z; v[7] = v1.w;
;                     emit(row0 + ai * 128 + m * 16, u.pn, colb + bj * 128, v);
;                 }
;     }
	v_cvt_pk_bf16_f32 v235, v68, v69
	v_lshl_add_u64 v[238:239], v[144:145], 0, v[226:227]
	global_store_dwordx4 v[238:239], v[232:235], off offset:256
	v_pk_add_f32 v[62:63], v[62:63], v[210:211]
	v_pk_add_f32 v[64:65], v[64:65], v[212:213]
	v_pk_add_f32 v[58:59], v[58:59], v[214:215]
	v_pk_add_f32 v[60:61], v[60:61], v[216:217]
	v_mul_f32_e32 v62, 0xbfb8aa3b, v62
	v_mul_f32_e32 v63, 0xbfb8aa3b, v63
	v_mul_f32_e32 v64, 0xbfb8aa3b, v64
	v_mul_f32_e32 v65, 0xbfb8aa3b, v65
	v_mul_f32_e32 v58, 0xbfb8aa3b, v58
	v_mul_f32_e32 v59, 0xbfb8aa3b, v59
	v_mul_f32_e32 v60, 0xbfb8aa3b, v60
	v_mul_f32_e32 v61, 0xbfb8aa3b, v61
	v_exp_f32_e32 v62, v62
	v_exp_f32_e32 v63, v63
	v_exp_f32_e32 v64, v64
	v_exp_f32_e32 v65, v65
	v_exp_f32_e32 v58, v58
	v_exp_f32_e32 v59, v59
	v_exp_f32_e32 v60, v60
	v_exp_f32_e32 v61, v61
	v_add_f32_e32 v62, 1.0, v62
	v_add_f32_e32 v63, 1.0, v63
	v_add_f32_e32 v64, 1.0, v64
	v_add_f32_e32 v65, 1.0, v65
	v_add_f32_e32 v58, 1.0, v58
	v_add_f32_e32 v59, 1.0, v59
	v_add_f32_e32 v60, 1.0, v60
	v_add_f32_e32 v61, 1.0, v61
	v_rcp_f32_e32 v62, v62
	v_rcp_f32_e32 v63, v63
	v_rcp_f32_e32 v64, v64
	v_rcp_f32_e32 v65, v65
	v_rcp_f32_e32 v58, v58
	v_rcp_f32_e32 v59, v59
	v_rcp_f32_e32 v60, v60
	v_rcp_f32_e32 v61, v61
	s_nop 0
	v_cvt_pk_bf16_f32 v228, v62, v63
	v_cvt_pk_bf16_f32 v229, v64, v65
	v_cvt_pk_bf16_f32 v230, v58, v59
	v_cvt_pk_bf16_f32 v231, v60, v61
	v_lshl_add_u64 v[236:237], v[146:147], 0, v[226:227]
	global_store_dwordx4 v[236:237], v[228:231], off
	v_pk_add_f32 v[54:55], v[54:55], v[218:219]
	v_pk_add_f32 v[56:57], v[56:57], v[220:221]
	v_pk_add_f32 v[50:51], v[50:51], v[222:223]
	v_pk_add_f32 v[52:53], v[52:53], v[224:225]
	v_mul_f32_e32 v54, 0xbfb8aa3b, v54
	v_mul_f32_e32 v55, 0xbfb8aa3b, v55
	v_mul_f32_e32 v56, 0xbfb8aa3b, v56
	v_mul_f32_e32 v57, 0xbfb8aa3b, v57
	v_mul_f32_e32 v50, 0xbfb8aa3b, v50
	v_mul_f32_e32 v51, 0xbfb8aa3b, v51
	v_mul_f32_e32 v52, 0xbfb8aa3b, v52
	v_mul_f32_e32 v53, 0xbfb8aa3b, v53
	v_exp_f32_e32 v54, v54
	v_exp_f32_e32 v55, v55
	v_exp_f32_e32 v56, v56
	v_exp_f32_e32 v57, v57
	v_exp_f32_e32 v50, v50
	v_exp_f32_e32 v51, v51
	v_exp_f32_e32 v52, v52
	v_exp_f32_e32 v53, v53
	v_add_f32_e32 v54, 1.0, v54
	v_add_f32_e32 v55, 1.0, v55
	v_add_f32_e32 v56, 1.0, v56
	v_add_f32_e32 v57, 1.0, v57
	v_add_f32_e32 v50, 1.0, v50
	v_add_f32_e32 v51, 1.0, v51
	v_add_f32_e32 v52, 1.0, v52
	v_add_f32_e32 v53, 1.0, v53
	v_rcp_f32_e32 v54, v54
	v_rcp_f32_e32 v55, v55
	v_rcp_f32_e32 v56, v56
	v_rcp_f32_e32 v57, v57
	v_rcp_f32_e32 v50, v50
	v_rcp_f32_e32 v51, v51
	v_rcp_f32_e32 v52, v52
	v_rcp_f32_e32 v53, v53
	s_nop 0
	v_cvt_pk_bf16_f32 v232, v54, v55
	v_cvt_pk_bf16_f32 v233, v56, v57
	v_cvt_pk_bf16_f32 v234, v50, v51
	v_cvt_pk_bf16_f32 v235, v52, v53
	v_lshl_add_u64 v[238:239], v[146:147], 0, v[226:227]
	global_store_dwordx4 v[238:239], v[232:235], off offset:256
	v_pk_add_f32 v[46:47], v[46:47], v[210:211]
	v_pk_add_f32 v[48:49], v[48:49], v[212:213]
	v_pk_add_f32 v[42:43], v[42:43], v[214:215]
	v_pk_add_f32 v[44:45], v[44:45], v[216:217]
	v_mul_f32_e32 v46, 0xbfb8aa3b, v46
	v_mul_f32_e32 v47, 0xbfb8aa3b, v47
	v_mul_f32_e32 v48, 0xbfb8aa3b, v48
	v_mul_f32_e32 v49, 0xbfb8aa3b, v49
	v_mul_f32_e32 v42, 0xbfb8aa3b, v42
	v_mul_f32_e32 v43, 0xbfb8aa3b, v43
	v_mul_f32_e32 v44, 0xbfb8aa3b, v44
	v_mul_f32_e32 v45, 0xbfb8aa3b, v45
	v_exp_f32_e32 v46, v46
	v_exp_f32_e32 v47, v47
	v_exp_f32_e32 v48, v48
	v_exp_f32_e32 v49, v49
	v_exp_f32_e32 v42, v42
	v_exp_f32_e32 v43, v43
	v_exp_f32_e32 v44, v44
	v_exp_f32_e32 v45, v45
	v_add_f32_e32 v46, 1.0, v46
	v_add_f32_e32 v47, 1.0, v47
	v_add_f32_e32 v48, 1.0, v48
	v_add_f32_e32 v49, 1.0, v49
	v_add_f32_e32 v42, 1.0, v42
	v_add_f32_e32 v43, 1.0, v43
	v_add_f32_e32 v44, 1.0, v44
	v_add_f32_e32 v45, 1.0, v45
	v_rcp_f32_e32 v46, v46
	v_rcp_f32_e32 v47, v47
	v_rcp_f32_e32 v48, v48
	v_rcp_f32_e32 v49, v49
	v_rcp_f32_e32 v42, v42
	v_rcp_f32_e32 v43, v43
	v_rcp_f32_e32 v44, v44
	v_rcp_f32_e32 v45, v45
	s_nop 0
	v_cvt_pk_bf16_f32 v228, v46, v47
	v_cvt_pk_bf16_f32 v229, v48, v49
	v_cvt_pk_bf16_f32 v230, v42, v43
	v_cvt_pk_bf16_f32 v231, v44, v45
	v_lshl_add_u64 v[236:237], v[148:149], 0, v[226:227]
	global_store_dwordx4 v[236:237], v[228:231], off
	v_pk_add_f32 v[38:39], v[38:39], v[218:219]
	v_pk_add_f32 v[40:41], v[40:41], v[220:221]
	v_pk_add_f32 v[34:35], v[34:35], v[222:223]
	v_pk_add_f32 v[36:37], v[36:37], v[224:225]
	v_mul_f32_e32 v38, 0xbfb8aa3b, v38
	v_mul_f32_e32 v39, 0xbfb8aa3b, v39
	v_mul_f32_e32 v40, 0xbfb8aa3b, v40
	v_mul_f32_e32 v41, 0xbfb8aa3b, v41
	v_mul_f32_e32 v34, 0xbfb8aa3b, v34
	v_mul_f32_e32 v35, 0xbfb8aa3b, v35
	v_mul_f32_e32 v36, 0xbfb8aa3b, v36
	v_mul_f32_e32 v37, 0xbfb8aa3b, v37
	v_exp_f32_e32 v38, v38
	v_exp_f32_e32 v39, v39
	v_exp_f32_e32 v40, v40
	v_exp_f32_e32 v41, v41
	v_exp_f32_e32 v34, v34
	v_exp_f32_e32 v35, v35
	v_exp_f32_e32 v36, v36
	v_exp_f32_e32 v37, v37
	v_add_f32_e32 v38, 1.0, v38
	v_add_f32_e32 v39, 1.0, v39
	v_add_f32_e32 v40, 1.0, v40
	v_add_f32_e32 v41, 1.0, v41
	v_add_f32_e32 v34, 1.0, v34
	v_add_f32_e32 v35, 1.0, v35
	v_add_f32_e32 v36, 1.0, v36
	v_add_f32_e32 v37, 1.0, v37
	v_rcp_f32_e32 v38, v38
	v_rcp_f32_e32 v39, v39
	v_rcp_f32_e32 v40, v40
	v_rcp_f32_e32 v41, v41
	v_rcp_f32_e32 v34, v34
	v_rcp_f32_e32 v35, v35
	v_rcp_f32_e32 v36, v36
	v_rcp_f32_e32 v37, v37
	s_nop 0
	v_cvt_pk_bf16_f32 v232, v38, v39
	v_cvt_pk_bf16_f32 v233, v40, v41
	v_cvt_pk_bf16_f32 v234, v34, v35
	v_cvt_pk_bf16_f32 v235, v36, v37
	v_lshl_add_u64 v[238:239], v[148:149], 0, v[226:227]
; __device__ __forceinline__ float sigmoidf_(float x) { return __builtin_amdgcn_rcpf(1.f + __expf(-x)); }
;     __device__ __forceinline__ void emit(int row, int pn, int col0, float* v) const {
;     ...
;             else { const int cg_ = col0 - 3840; const f32x4 b0 = ldg<f32x4>(f0 + cg_), b1 = ldg<f32x4>(f0 + cg_ + 4);
;                 v[0] = sigmoidf_(v[0] + b0.x); v[1] = sigmoidf_(v[1] + b0.y); v[2] = sigmoidf_(v[2] + b0.z); v[3] = sigmoidf_(v[3] + b0.w);
;                 v[4] = sigmoidf_(v[4] + b1.x); v[5] = sigmoidf_(v[5] + b1.y); v[6] = sigmoidf_(v[6] + b1.z); v[7] = sigmoidf_(v[7] + b1.w);
;                 store8((bf16_t*)(ws + WS_GATE) + (size_t)row * GT_COLS + cg_, v); }
	global_store_dwordx4 v[238:239], v[232:235], off offset:256
	v_pk_add_f32 v[30:31], v[30:31], v[210:211]
	v_pk_add_f32 v[32:33], v[32:33], v[212:213]
	v_pk_add_f32 v[26:27], v[26:27], v[214:215]
	v_pk_add_f32 v[28:29], v[28:29], v[216:217]
	v_mul_f32_e32 v30, 0xbfb8aa3b, v30
	v_mul_f32_e32 v31, 0xbfb8aa3b, v31
	v_mul_f32_e32 v32, 0xbfb8aa3b, v32
	v_mul_f32_e32 v33, 0xbfb8aa3b, v33
	v_mul_f32_e32 v26, 0xbfb8aa3b, v26
	v_mul_f32_e32 v27, 0xbfb8aa3b, v27
	v_mul_f32_e32 v28, 0xbfb8aa3b, v28
	v_mul_f32_e32 v29, 0xbfb8aa3b, v29
	v_exp_f32_e32 v30, v30
	v_exp_f32_e32 v31, v31
	v_exp_f32_e32 v32, v32
	v_exp_f32_e32 v33, v33
	v_exp_f32_e32 v26, v26
	v_exp_f32_e32 v27, v27
	v_exp_f32_e32 v28, v28
	v_exp_f32_e32 v29, v29
	v_add_f32_e32 v30, 1.0, v30
	v_add_f32_e32 v31, 1.0, v31
	v_add_f32_e32 v32, 1.0, v32
	v_add_f32_e32 v33, 1.0, v33
	v_add_f32_e32 v26, 1.0, v26
	v_add_f32_e32 v27, 1.0, v27
	v_add_f32_e32 v28, 1.0, v28
	v_add_f32_e32 v29, 1.0, v29
	v_rcp_f32_e32 v30, v30
	v_rcp_f32_e32 v31, v31
	v_rcp_f32_e32 v32, v32
	v_rcp_f32_e32 v33, v33
	v_rcp_f32_e32 v26, v26
	v_rcp_f32_e32 v27, v27
	v_rcp_f32_e32 v28, v28
	v_rcp_f32_e32 v29, v29
	s_nop 0
	v_cvt_pk_bf16_f32 v228, v30, v31
	v_cvt_pk_bf16_f32 v229, v32, v33
	v_cvt_pk_bf16_f32 v230, v26, v27
	v_cvt_pk_bf16_f32 v231, v28, v29
	v_lshl_add_u64 v[236:237], v[150:151], 0, v[226:227]
	global_store_dwordx4 v[236:237], v[228:231], off
	v_pk_add_f32 v[22:23], v[22:23], v[218:219]
	v_pk_add_f32 v[24:25], v[24:25], v[220:221]
	v_pk_add_f32 v[18:19], v[18:19], v[222:223]
	v_pk_add_f32 v[20:21], v[20:21], v[224:225]
	v_mul_f32_e32 v22, 0xbfb8aa3b, v22
	v_mul_f32_e32 v23, 0xbfb8aa3b, v23
	v_mul_f32_e32 v24, 0xbfb8aa3b, v24
	v_mul_f32_e32 v25, 0xbfb8aa3b, v25
	v_mul_f32_e32 v18, 0xbfb8aa3b, v18
	v_mul_f32_e32 v19, 0xbfb8aa3b, v19
	v_mul_f32_e32 v20, 0xbfb8aa3b, v20
	v_mul_f32_e32 v21, 0xbfb8aa3b, v21
	v_exp_f32_e32 v22, v22
	v_exp_f32_e32 v23, v23
	v_exp_f32_e32 v24, v24
	v_exp_f32_e32 v25, v25
	v_exp_f32_e32 v18, v18
	v_exp_f32_e32 v19, v19
	v_exp_f32_e32 v20, v20
	v_exp_f32_e32 v21, v21
	v_add_f32_e32 v22, 1.0, v22
	v_add_f32_e32 v23, 1.0, v23
	v_add_f32_e32 v24, 1.0, v24
	v_add_f32_e32 v25, 1.0, v25
	v_add_f32_e32 v18, 1.0, v18
	v_add_f32_e32 v19, 1.0, v19
	v_add_f32_e32 v20, 1.0, v20
	v_add_f32_e32 v21, 1.0, v21
	v_rcp_f32_e32 v22, v22
	v_rcp_f32_e32 v23, v23
	v_rcp_f32_e32 v24, v24
	v_rcp_f32_e32 v25, v25
	v_rcp_f32_e32 v18, v18
	v_rcp_f32_e32 v19, v19
	v_rcp_f32_e32 v20, v20
	v_rcp_f32_e32 v21, v21
	s_nop 0
	v_cvt_pk_bf16_f32 v232, v22, v23
	v_cvt_pk_bf16_f32 v233, v24, v25
	v_cvt_pk_bf16_f32 v234, v18, v19
	v_cvt_pk_bf16_f32 v235, v20, v21
	v_lshl_add_u64 v[238:239], v[150:151], 0, v[226:227]
	global_store_dwordx4 v[238:239], v[232:235], off offset:256
	v_pk_add_f32 v[14:15], v[14:15], v[210:211]
	v_pk_add_f32 v[16:17], v[16:17], v[212:213]
	v_pk_add_f32 v[10:11], v[10:11], v[214:215]
	v_pk_add_f32 v[12:13], v[12:13], v[216:217]
	v_mul_f32_e32 v14, 0xbfb8aa3b, v14
	v_mul_f32_e32 v15, 0xbfb8aa3b, v15
	v_mul_f32_e32 v16, 0xbfb8aa3b, v16
	v_mul_f32_e32 v17, 0xbfb8aa3b, v17
	v_mul_f32_e32 v10, 0xbfb8aa3b, v10
	v_mul_f32_e32 v11, 0xbfb8aa3b, v11
	v_mul_f32_e32 v12, 0xbfb8aa3b, v12
	v_mul_f32_e32 v13, 0xbfb8aa3b, v13
	v_exp_f32_e32 v14, v14
	v_exp_f32_e32 v15, v15
	v_exp_f32_e32 v16, v16
	v_exp_f32_e32 v17, v17
	v_exp_f32_e32 v10, v10
	v_exp_f32_e32 v11, v11
	v_exp_f32_e32 v12, v12
	v_exp_f32_e32 v13, v13
	v_add_f32_e32 v14, 1.0, v14
	v_add_f32_e32 v15, 1.0, v15
	v_add_f32_e32 v16, 1.0, v16
	v_add_f32_e32 v17, 1.0, v17
	v_add_f32_e32 v10, 1.0, v10
	v_add_f32_e32 v11, 1.0, v11
	v_add_f32_e32 v12, 1.0, v12
	v_add_f32_e32 v13, 1.0, v13
	v_rcp_f32_e32 v14, v14
	v_rcp_f32_e32 v15, v15
	v_rcp_f32_e32 v16, v16
	v_rcp_f32_e32 v17, v17
	v_rcp_f32_e32 v10, v10
	v_rcp_f32_e32 v11, v11
	v_rcp_f32_e32 v12, v12
	v_rcp_f32_e32 v13, v13
	s_nop 0
	v_cvt_pk_bf16_f32 v228, v14, v15
	v_cvt_pk_bf16_f32 v229, v16, v17
	v_cvt_pk_bf16_f32 v230, v10, v11
	v_cvt_pk_bf16_f32 v231, v12, v13
	v_lshl_add_u64 v[236:237], v[152:153], 0, v[226:227]
	global_store_dwordx4 v[236:237], v[228:231], off
	v_pk_add_f32 v[6:7], v[6:7], v[218:219]
	v_pk_add_f32 v[8:9], v[8:9], v[220:221]
	v_pk_add_f32 v[2:3], v[2:3], v[222:223]
	v_pk_add_f32 v[4:5], v[4:5], v[224:225]
	v_mul_f32_e32 v6, 0xbfb8aa3b, v6
	v_mul_f32_e32 v7, 0xbfb8aa3b, v7
	v_mul_f32_e32 v8, 0xbfb8aa3b, v8
	v_mul_f32_e32 v9, 0xbfb8aa3b, v9
	v_mul_f32_e32 v2, 0xbfb8aa3b, v2
	v_mul_f32_e32 v3, 0xbfb8aa3b, v3
	v_mul_f32_e32 v4, 0xbfb8aa3b, v4
	v_mul_f32_e32 v5, 0xbfb8aa3b, v5
	v_exp_f32_e32 v6, v6
	v_exp_f32_e32 v7, v7
	v_exp_f32_e32 v8, v8
	v_exp_f32_e32 v9, v9
	v_exp_f32_e32 v2, v2
	v_exp_f32_e32 v3, v3
	v_exp_f32_e32 v4, v4
	v_exp_f32_e32 v5, v5
	v_add_f32_e32 v6, 1.0, v6
	v_add_f32_e32 v7, 1.0, v7
	v_add_f32_e32 v8, 1.0, v8
	v_add_f32_e32 v9, 1.0, v9
	v_add_f32_e32 v2, 1.0, v2
	v_add_f32_e32 v3, 1.0, v3
	v_add_f32_e32 v4, 1.0, v4
	v_add_f32_e32 v5, 1.0, v5
	v_rcp_f32_e32 v6, v6
	v_rcp_f32_e32 v7, v7
	v_rcp_f32_e32 v8, v8
	v_rcp_f32_e32 v9, v9
	v_rcp_f32_e32 v2, v2
	v_rcp_f32_e32 v3, v3
	v_rcp_f32_e32 v4, v4
	v_rcp_f32_e32 v5, v5
	s_nop 0
	v_cvt_pk_bf16_f32 v232, v6, v7
	v_cvt_pk_bf16_f32 v233, v8, v9
	v_cvt_pk_bf16_f32 v234, v2, v3
	v_cvt_pk_bf16_f32 v235, v4, v5
	v_lshl_add_u64 v[238:239], v[152:153], 0, v[226:227]
	global_store_dwordx4 v[238:239], v[232:235], off offset:256
	s_mov_b32 s22, 1
	s_mov_b64 s[2:3], 0
	s_and_b64 vcc, exec, s[38:39]
	s_cbranch_vccz .LBB0_229
	s_branch .Lgt_tail

; #define PG8_STAGE(bufoff, gbase, voff) do { _Pragma("unroll") for (int _i = 0; _i < 2; ++_i) \
;         __builtin_amdgcn_global_load_lds((const unsigned*)((const char*)(gbase) + (voff)[_i]), (PG8_LAS unsigned*)(lds + (bufoff) + ldsw + _i * 8192), 16, 0, 0); } while (0)
; #define PG8_LDA(dst, b, h) do { _Pragma("unroll") for (int m = 0; m < 4; ++m) _Pragma("unroll") for (int k = 0; k < 2; ++k) dst[m][k] = *(const PG8_LAS bf16x8*)(lds + PG8_SA(b, h) + aoff + m * 2048 + k * 1024); } while (0)
; #define PG8_LDB(dst, b, h) do { _Pragma("unroll") for (int n = 0; n < 2; ++n) _Pragma("unroll") for (int k = 0; k < 2; ++k) dst[n][k] = *(const PG8_LAS bf16x8*)(lds + PG8_SB(b, h) + boff + n * 2048 + k * 1024); } while (0)
; #define PG8_MMA(ai, bj, At, Bt) do { __builtin_amdgcn_s_setprio(1); _Pragma("unroll") for (int m = 0; m < 4; ++m) _Pragma("unroll") for (int n = 0; n < 2; ++n) _Pragma("unroll") for (int k = 0; k < 2; ++k) \
;         acc[ai][bj][m][n] = __builtin_amdgcn_mfma_f32_16x16x32_bf16(Bt[n][k], At[m][k], acc[ai][bj][m][n], 0, 0, 0); __builtin_amdgcn_s_setprio(0); } while (0)
; #define PG8_WAIT_V(n) asm volatile("s_waitcnt vmcnt(" #n ")" ::: "memory")
; #define PG8_WAIT_L(n) asm volatile("s_waitcnt lgkmcnt(" #n ")" ::: "memory")
; #define PG8_BAR __builtin_amdgcn_s_barrier()
; #define PG8_SCHED __builtin_amdgcn_sched_barrier(0)
; template <class Epi, class Sched, bool ALIGN_EPI = false, bool SP2 = false>
; __device__ __forceinline__ void gemm_phase(PG8_LAS unsigned char* lds, const Gemm g, const Sched& S, const Epi& E) {
;     ...
;             PG8_LDB(B0, 0, 0); PG8_LDB(B1, 0, 1); PG8_SCHED; PG8_LDA(At, 0, 0); PG8_STAGE(PG8_SA(1, 1), a1 + hstepA, voffA);
;             PG8_WAIT_V(8); PG8_WAIT_L(0); PG8_BAR; PG8_MMA(0, 0, At, B0); PG8_MMA(0, 1, At, B1); PG8_BAR; PG8_SCHED;
;             PG8_LDA(At, 0, 1); PG8_STAGE(PG8_SB(0, 0), b2, voffB); PG8_STAGE(PG8_SB(0, 1), b2 + hstepB, voffB); PG8_STAGE(PG8_SA(0, 0), a2, voffA);
;             PG8_WAIT_V(8); PG8_WAIT_L(0); PG8_BAR; PG8_MMA(1, 0, At, B0); PG8_MMA(1, 1, At, B1); PG8_BAR; PG8_SCHED;
.LBB0_230:
	s_add_u32 s20, s45, s2
	s_addc_u32 s21, s46, s3
	s_add_u32 s20, s20, 0x2d00100
	s_addc_u32 s21, s21, 0
	s_add_u32 s49, s17, s2
	s_addc_u32 s50, s19, s3
	s_add_i32 s51, 0, 0x10000
	s_cmpk_eq_i32 s2, 0x700
	s_cselect_b32 s25, s5, s21
	s_cselect_b32 s24, s4, s20
	v_add_u32_e32 v0, s51, v160
	s_cselect_b32 s21, s14, s50
	s_cselect_b32 s20, s15, s49
	s_add_i32 s49, 0, 0x14000
	ds_read_b128 v[164:167], v0
	ds_read_b128 v[168:171], v0 offset:1024
	ds_read_b128 v[172:175], v0 offset:2048
	ds_read_b128 v[180:183], v0 offset:3072
	v_add_u32_e32 v0, s49, v160
	ds_read_b128 v[184:187], v0
	ds_read_b128 v[188:191], v0 offset:1024
	ds_read_b128 v[210:213], v0 offset:2048
	ds_read_b128 v[214:217], v0 offset:3072
	v_lshl_add_u64 v[158:159], v[156:157], 0, s[2:3]
	s_add_i32 m0, s30, 0xc000
	ds_read_b128 v[218:221], v162
	ds_read_b128 v[222:225], v162 offset:1024
	ds_read_b128 v[226:229], v162 offset:2048
	ds_read_b128 v[230:233], v162 offset:3072
	ds_read_b128 v[234:237], v162 offset:4096
	ds_read_b128 v[238:241], v162 offset:5120
	ds_read_b128 v[242:245], v162 offset:6144
	ds_read_b128 v[246:249], v162 offset:7168
	global_load_lds_dwordx4 v[158:159], off
	v_lshl_add_u64 v[158:159], v[154:155], 0, s[2:3]
	s_add_i32 m0, s30, 0xe000
	s_nop 0
	global_load_lds_dwordx4 v[158:159], off
	s_waitcnt vmcnt(8)
	s_waitcnt lgkmcnt(0)
	s_barrier
	s_setprio 1
	s_waitcnt lgkmcnt(0)
	v_mfma_f32_16x16x32_bf16 v[126:129], v[164:167], v[218:221], v[126:129]
	v_mfma_f32_16x16x32_bf16 v[122:125], v[172:175], v[218:221], v[122:125]
	v_mfma_f32_16x16x32_bf16 v[110:113], v[164:167], v[226:229], v[110:113]
	v_mfma_f32_16x16x32_bf16 v[106:109], v[172:175], v[226:229], v[106:109]
	v_mfma_f32_16x16x32_bf16 v[94:97], v[164:167], v[234:237], v[94:97]
	v_mfma_f32_16x16x32_bf16 v[90:93], v[172:175], v[234:237], v[90:93]
	v_mfma_f32_16x16x32_bf16 v[78:81], v[164:167], v[242:245], v[78:81]
	v_mfma_f32_16x16x32_bf16 v[74:77], v[172:175], v[242:245], v[74:77]
	v_mfma_f32_16x16x32_bf16 v[126:129], v[168:171], v[222:225], v[126:129]
	v_mfma_f32_16x16x32_bf16 v[122:125], v[180:183], v[222:225], v[122:125]
	v_mfma_f32_16x16x32_bf16 v[110:113], v[168:171], v[230:233], v[110:113]
	v_mfma_f32_16x16x32_bf16 v[106:109], v[180:183], v[230:233], v[106:109]
	v_mfma_f32_16x16x32_bf16 v[94:97], v[168:171], v[238:241], v[94:97]
	v_mfma_f32_16x16x32_bf16 v[90:93], v[180:183], v[238:241], v[90:93]
	v_mfma_f32_16x16x32_bf16 v[78:81], v[168:171], v[246:249], v[78:81]
	v_mfma_f32_16x16x32_bf16 v[74:77], v[180:183], v[246:249], v[74:77]
	s_setprio 0
	s_setprio 1
	v_mfma_f32_16x16x32_bf16 v[118:121], v[184:187], v[218:221], v[118:121]
	v_mfma_f32_16x16x32_bf16 v[114:117], v[210:213], v[218:221], v[114:117]
	v_mfma_f32_16x16x32_bf16 v[102:105], v[184:187], v[226:229], v[102:105]
	v_mfma_f32_16x16x32_bf16 v[98:101], v[210:213], v[226:229], v[98:101]
	v_mfma_f32_16x16x32_bf16 v[86:89], v[184:187], v[234:237], v[86:89]
	v_mfma_f32_16x16x32_bf16 v[82:85], v[210:213], v[234:237], v[82:85]
	v_mfma_f32_16x16x32_bf16 v[70:73], v[184:187], v[242:245], v[70:73]
	v_mfma_f32_16x16x32_bf16 v[66:69], v[210:213], v[242:245], v[66:69]
	v_mfma_f32_16x16x32_bf16 v[118:121], v[188:191], v[222:225], v[118:121]
	v_mfma_f32_16x16x32_bf16 v[114:117], v[214:217], v[222:225], v[114:117]
	v_mfma_f32_16x16x32_bf16 v[102:105], v[188:191], v[230:233], v[102:105]
	v_mfma_f32_16x16x32_bf16 v[98:101], v[214:217], v[230:233], v[98:101]
	v_mfma_f32_16x16x32_bf16 v[86:89], v[188:191], v[238:241], v[86:89]
	v_mfma_f32_16x16x32_bf16 v[82:85], v[214:217], v[238:241], v[82:85]
	v_mfma_f32_16x16x32_bf16 v[70:73], v[188:191], v[246:249], v[70:73]
	v_mfma_f32_16x16x32_bf16 v[66:69], v[214:217], v[246:249], v[66:69]
	s_setprio 0
	s_barrier
	s_add_i32 s50, s51, s29
	v_lshl_add_u64 v[158:159], s[20:21], 0, v[134:135]
	s_mov_b32 m0, s50
	ds_read_b128 v[218:221], v162 offset:16384
	ds_read_b128 v[222:225], v162 offset:17408
	ds_read_b128 v[226:229], v162 offset:18432
	ds_read_b128 v[230:233], v162 offset:19456
	ds_read_b128 v[234:237], v162 offset:20480
	ds_read_b128 v[238:241], v162 offset:21504
	ds_read_b128 v[242:245], v162 offset:22528
	ds_read_b128 v[246:249], v162 offset:23552
	global_load_lds_dwordx4 v[158:159], off
	s_add_i32 m0, s50, 0x2000
	s_add_u32 s50, s20, 0x40000
	v_lshl_add_u64 v[176:177], s[20:21], 0, v[130:131]
	s_addc_u32 s51, s21, 0
	s_add_i32 s49, s49, s29
	global_load_lds_dwordx4 v[176:177], off
	v_lshl_add_u64 v[250:251], s[50:51], 0, v[134:135]
	s_mov_b32 m0, s49
	v_lshl_add_u64 v[200:201], s[24:25], 0, v[132:133]
	global_load_lds_dwordx4 v[250:251], off
	v_lshl_add_u64 v[250:251], s[50:51], 0, v[130:131]
	s_add_i32 m0, s49, 0x2000
	s_nop 0
	global_load_lds_dwordx4 v[250:251], off
	v_lshl_add_u64 v[250:251], s[24:25], 0, v[136:137]
	s_mov_b32 m0, s30
	s_nop 0
	global_load_lds_dwordx4 v[250:251], off
	s_mov_b32 m0, s31
	s_nop 0
	global_load_lds_dwordx4 v[200:201], off
	s_waitcnt vmcnt(8)
	s_waitcnt lgkmcnt(0)
	s_barrier
; #define PG8_STAGE(bufoff, gbase, voff) do { _Pragma("unroll") for (int _i = 0; _i < 2; ++_i) \
;         __builtin_amdgcn_global_load_lds((const unsigned*)((const char*)(gbase) + (voff)[_i]), (PG8_LAS unsigned*)(lds + (bufoff) + ldsw + _i * 8192), 16, 0, 0); } while (0)
; #define PG8_LDA(dst, b, h) do { _Pragma("unroll") for (int m = 0; m < 4; ++m) _Pragma("unroll") for (int k = 0; k < 2; ++k) dst[m][k] = *(const PG8_LAS bf16x8*)(lds + PG8_SA(b, h) + aoff + m * 2048 + k * 1024); } while (0)
; #define PG8_LDB(dst, b, h) do { _Pragma("unroll") for (int n = 0; n < 2; ++n) _Pragma("unroll") for (int k = 0; k < 2; ++k) dst[n][k] = *(const PG8_LAS bf16x8*)(lds + PG8_SB(b, h) + boff + n * 2048 + k * 1024); } while (0)
; #define PG8_MMA(ai, bj, At, Bt) do { __builtin_amdgcn_s_setprio(1); _Pragma("unroll") for (int m = 0; m < 4; ++m) _Pragma("unroll") for (int n = 0; n < 2; ++n) _Pragma("unroll") for (int k = 0; k < 2; ++k) \
;         acc[ai][bj][m][n] = __builtin_amdgcn_mfma_f32_16x16x32_bf16(Bt[n][k], At[m][k], acc[ai][bj][m][n], 0, 0, 0); __builtin_amdgcn_s_setprio(0); } while (0)
; #define PG8_WAIT_V(n) asm volatile("s_waitcnt vmcnt(" #n ")" ::: "memory")
; #define PG8_WAIT_L(n) asm volatile("s_waitcnt lgkmcnt(" #n ")" ::: "memory")
; #define PG8_BAR __builtin_amdgcn_s_barrier()
; #define PG8_SCHED __builtin_amdgcn_sched_barrier(0)
; template <class Epi, class Sched, bool ALIGN_EPI = false, bool SP2 = false>
; __device__ __forceinline__ void gemm_phase(PG8_LAS unsigned char* lds, const Gemm g, const Sched& S, const Epi& E) {
;     ...
;             PG8_WAIT_V(8); PG8_WAIT_L(0); PG8_BAR; PG8_MMA(1, 0, At, B0); PG8_MMA(1, 1, At, B1); PG8_BAR; PG8_SCHED;
;             PG8_LDB(B0, 1, 0); PG8_LDB(B1, 1, 1); PG8_SCHED; PG8_LDA(At, 1, 0); PG8_STAGE(PG8_SA(0, 1), a2 + hstepA, voffA);
;             PG8_WAIT_V(8); PG8_WAIT_L(0); PG8_BAR; PG8_MMA(0, 0, At, B0); PG8_MMA(0, 1, At, B1); PG8_BAR; PG8_SCHED;
	s_setprio 1
	s_waitcnt lgkmcnt(0)
	v_mfma_f32_16x16x32_bf16 v[62:65], v[164:167], v[218:221], v[62:65]
	v_mfma_f32_16x16x32_bf16 v[58:61], v[172:175], v[218:221], v[58:61]
	v_mfma_f32_16x16x32_bf16 v[46:49], v[164:167], v[226:229], v[46:49]
	v_mfma_f32_16x16x32_bf16 v[42:45], v[172:175], v[226:229], v[42:45]
	v_mfma_f32_16x16x32_bf16 v[30:33], v[164:167], v[234:237], v[30:33]
	v_mfma_f32_16x16x32_bf16 v[26:29], v[172:175], v[234:237], v[26:29]
	v_mfma_f32_16x16x32_bf16 v[14:17], v[164:167], v[242:245], v[14:17]
	v_mfma_f32_16x16x32_bf16 v[10:13], v[172:175], v[242:245], v[10:13]
	v_mfma_f32_16x16x32_bf16 v[62:65], v[168:171], v[222:225], v[62:65]
	v_mfma_f32_16x16x32_bf16 v[58:61], v[180:183], v[222:225], v[58:61]
	v_mfma_f32_16x16x32_bf16 v[46:49], v[168:171], v[230:233], v[46:49]
	v_mfma_f32_16x16x32_bf16 v[42:45], v[180:183], v[230:233], v[42:45]
	v_mfma_f32_16x16x32_bf16 v[30:33], v[168:171], v[238:241], v[30:33]
	v_mfma_f32_16x16x32_bf16 v[26:29], v[180:183], v[238:241], v[26:29]
	v_mfma_f32_16x16x32_bf16 v[14:17], v[168:171], v[246:249], v[14:17]
	v_mfma_f32_16x16x32_bf16 v[10:13], v[180:183], v[246:249], v[10:13]
	s_setprio 0
	s_setprio 1
	v_mfma_f32_16x16x32_bf16 v[54:57], v[184:187], v[218:221], v[54:57]
	v_mfma_f32_16x16x32_bf16 v[50:53], v[210:213], v[218:221], v[50:53]
	v_mfma_f32_16x16x32_bf16 v[38:41], v[184:187], v[226:229], v[38:41]
	v_mfma_f32_16x16x32_bf16 v[34:37], v[210:213], v[226:229], v[34:37]
	v_mfma_f32_16x16x32_bf16 v[22:25], v[184:187], v[234:237], v[22:25]
	v_mfma_f32_16x16x32_bf16 v[18:21], v[210:213], v[234:237], v[18:21]
	v_mfma_f32_16x16x32_bf16 v[6:9], v[184:187], v[242:245], v[6:9]
	v_mfma_f32_16x16x32_bf16 v[2:5], v[210:213], v[242:245], v[2:5]
	v_mfma_f32_16x16x32_bf16 v[54:57], v[188:191], v[222:225], v[54:57]
	v_mfma_f32_16x16x32_bf16 v[50:53], v[214:217], v[222:225], v[50:53]
	v_mfma_f32_16x16x32_bf16 v[38:41], v[188:191], v[230:233], v[38:41]
	v_mfma_f32_16x16x32_bf16 v[34:37], v[214:217], v[230:233], v[34:37]
	v_mfma_f32_16x16x32_bf16 v[22:25], v[188:191], v[238:241], v[22:25]
	v_mfma_f32_16x16x32_bf16 v[18:21], v[214:217], v[238:241], v[18:21]
	v_mfma_f32_16x16x32_bf16 v[6:9], v[188:191], v[246:249], v[6:9]
	v_mfma_f32_16x16x32_bf16 v[2:5], v[214:217], v[246:249], v[2:5]
	s_setprio 0
	s_barrier
	s_add_i32 s49, 0, 0x18000
	v_add_u32_e32 v0, s49, v160
	s_add_i32 s50, 0, 0x1c000
	ds_read_b128 v[164:167], v0
	ds_read_b128 v[168:171], v0 offset:1024
	ds_read_b128 v[172:175], v0 offset:2048
	ds_read_b128 v[180:183], v0 offset:3072
	v_add_u32_e32 v0, s50, v160
	ds_read_b128 v[184:187], v0
	ds_read_b128 v[188:191], v0 offset:1024
	ds_read_b128 v[210:213], v0 offset:2048
	ds_read_b128 v[214:217], v0 offset:3072
	s_add_u32 s24, s24, 0x40000
	s_addc_u32 s25, s25, 0
	s_mov_b32 m0, s40
	v_lshl_add_u64 v[202:203], s[24:25], 0, v[136:137]
	ds_read_b128 v[218:221], v162 offset:32768
	ds_read_b128 v[222:225], v162 offset:33792
	ds_read_b128 v[226:229], v162 offset:34816
	ds_read_b128 v[230:233], v162 offset:35840
	ds_read_b128 v[234:237], v162 offset:36864
	ds_read_b128 v[238:241], v162 offset:37888
	ds_read_b128 v[242:245], v162 offset:38912
	ds_read_b128 v[246:249], v162 offset:39936
	global_load_lds_dwordx4 v[202:203], off
	v_lshl_add_u64 v[202:203], s[24:25], 0, v[132:133]
	s_mov_b32 m0, s41
	s_nop 0
	global_load_lds_dwordx4 v[202:203], off
	s_waitcnt vmcnt(8)
	s_waitcnt lgkmcnt(0)
	s_barrier
	s_setprio 1
	s_waitcnt lgkmcnt(0)
	v_mfma_f32_16x16x32_bf16 v[126:129], v[164:167], v[218:221], v[126:129]
	v_mfma_f32_16x16x32_bf16 v[122:125], v[172:175], v[218:221], v[122:125]
	v_mfma_f32_16x16x32_bf16 v[110:113], v[164:167], v[226:229], v[110:113]
	v_mfma_f32_16x16x32_bf16 v[106:109], v[172:175], v[226:229], v[106:109]
	v_mfma_f32_16x16x32_bf16 v[94:97], v[164:167], v[234:237], v[94:97]
	v_mfma_f32_16x16x32_bf16 v[90:93], v[172:175], v[234:237], v[90:93]
	v_mfma_f32_16x16x32_bf16 v[78:81], v[164:167], v[242:245], v[78:81]
	v_mfma_f32_16x16x32_bf16 v[74:77], v[172:175], v[242:245], v[74:77]
	v_mfma_f32_16x16x32_bf16 v[126:129], v[168:171], v[222:225], v[126:129]
	v_mfma_f32_16x16x32_bf16 v[122:125], v[180:183], v[222:225], v[122:125]
	v_mfma_f32_16x16x32_bf16 v[110:113], v[168:171], v[230:233], v[110:113]
	v_mfma_f32_16x16x32_bf16 v[106:109], v[180:183], v[230:233], v[106:109]
	v_mfma_f32_16x16x32_bf16 v[94:97], v[168:171], v[238:241], v[94:97]
	v_mfma_f32_16x16x32_bf16 v[90:93], v[180:183], v[238:241], v[90:93]
	v_mfma_f32_16x16x32_bf16 v[78:81], v[168:171], v[246:249], v[78:81]
	v_mfma_f32_16x16x32_bf16 v[74:77], v[180:183], v[246:249], v[74:77]
	s_setprio 0
	s_setprio 1
	v_mfma_f32_16x16x32_bf16 v[118:121], v[184:187], v[218:221], v[118:121]
	v_mfma_f32_16x16x32_bf16 v[114:117], v[210:213], v[218:221], v[114:117]
	v_mfma_f32_16x16x32_bf16 v[102:105], v[184:187], v[226:229], v[102:105]
	v_mfma_f32_16x16x32_bf16 v[98:101], v[210:213], v[226:229], v[98:101]
	v_mfma_f32_16x16x32_bf16 v[86:89], v[184:187], v[234:237], v[86:89]
	v_mfma_f32_16x16x32_bf16 v[82:85], v[210:213], v[234:237], v[82:85]
	v_mfma_f32_16x16x32_bf16 v[70:73], v[184:187], v[242:245], v[70:73]
	v_mfma_f32_16x16x32_bf16 v[66:69], v[210:213], v[242:245], v[66:69]
	v_mfma_f32_16x16x32_bf16 v[118:121], v[188:191], v[222:225], v[118:121]
	v_mfma_f32_16x16x32_bf16 v[114:117], v[214:217], v[222:225], v[114:117]
	v_mfma_f32_16x16x32_bf16 v[102:105], v[188:191], v[230:233], v[102:105]
	v_mfma_f32_16x16x32_bf16 v[98:101], v[214:217], v[230:233], v[98:101]
	v_mfma_f32_16x16x32_bf16 v[86:89], v[188:191], v[238:241], v[86:89]
	v_mfma_f32_16x16x32_bf16 v[82:85], v[214:217], v[238:241], v[82:85]
	v_mfma_f32_16x16x32_bf16 v[70:73], v[188:191], v[246:249], v[70:73]
	v_mfma_f32_16x16x32_bf16 v[66:69], v[214:217], v[246:249], v[66:69]
	s_setprio 0
	s_barrier
; __device__ __forceinline__ float sigmoidf_(float x) { return __builtin_amdgcn_rcpf(1.f + __expf(-x)); }
; #define PG8_STAGE(bufoff, gbase, voff) do { _Pragma("unroll") for (int _i = 0; _i < 2; ++_i) \
;         __builtin_amdgcn_global_load_lds((const unsigned*)((const char*)(gbase) + (voff)[_i]), (PG8_LAS unsigned*)(lds + (bufoff) + ldsw + _i * 8192), 16, 0, 0); } while (0)
; #define PG8_LDA(dst, b, h) do { _Pragma("unroll") for (int m = 0; m < 4; ++m) _Pragma("unroll") for (int k = 0; k < 2; ++k) dst[m][k] = *(const PG8_LAS bf16x8*)(lds + PG8_SA(b, h) + aoff + m * 2048 + k * 1024); } while (0)
; #define PG8_MMA(ai, bj, At, Bt) do { __builtin_amdgcn_s_setprio(1); _Pragma("unroll") for (int m = 0; m < 4; ++m) _Pragma("unroll") for (int n = 0; n < 2; ++n) _Pragma("unroll") for (int k = 0; k < 2; ++k) \
;         acc[ai][bj][m][n] = __builtin_amdgcn_mfma_f32_16x16x32_bf16(Bt[n][k], At[m][k], acc[ai][bj][m][n], 0, 0, 0); __builtin_amdgcn_s_setprio(0); } while (0)
; #define PG8_WAIT_V(n) asm volatile("s_waitcnt vmcnt(" #n ")" ::: "memory")
; #define PG8_WAIT_L(n) asm volatile("s_waitcnt lgkmcnt(" #n ")" ::: "memory")
; #define PG8_BAR __builtin_amdgcn_s_barrier()
; #define PG8_SCHED __builtin_amdgcn_sched_barrier(0)
; template <class Epi, class Sched, bool ALIGN_EPI = false, bool SP2 = false>
; __device__ __forceinline__ void gemm_phase(PG8_LAS unsigned char* lds, const Gemm g, const Sched& S, const Epi& E) {
;     ...
;             PG8_LDA(At, 1, 1); PG8_STAGE(PG8_SB(1, 0), b3, voffB); PG8_STAGE(PG8_SB(1, 1), b3 + hstepB, voffB); PG8_STAGE(PG8_SA(1, 0), a3, voffA);
;             PG8_WAIT_V(8); PG8_WAIT_L(0); PG8_BAR; PG8_MMA(1, 0, At, B0); PG8_MMA(1, 1, At, B1); PG8_BAR; PG8_SCHED;
;     __device__ __forceinline__ void emit(int row, int pn, int col0, float* v) const {
;     ...
;             else { const int cg_ = col0 - 3840; const f32x4 b0 = ldg<f32x4>(f0 + cg_), b1 = ldg<f32x4>(f0 + cg_ + 4);
;                 v[0] = sigmoidf_(v[0] + b0.x); v[1] = sigmoidf_(v[1] + b0.y); v[2] = sigmoidf_(v[2] + b0.z); v[3] = sigmoidf_(v[3] + b0.w);
;                 v[4] = sigmoidf_(v[4] + b1.x); v[5] = sigmoidf_(v[5] + b1.y); v[6] = sigmoidf_(v[6] + b1.z); v[7] = sigmoidf_(v[7] + b1.w);
;                 store8((bf16_t*)(ws + WS_GATE) + (size_t)row * GT_COLS + cg_, v); }
	s_add_i32 s24, s49, s29
	v_lshl_add_u64 v[158:159], v[158:159], 0, s[34:35]
	s_mov_b32 m0, s24
	ds_read_b128 v[218:221], v162 offset:49152
	ds_read_b128 v[222:225], v162 offset:50176
	ds_read_b128 v[226:229], v162 offset:51200
	ds_read_b128 v[230:233], v162 offset:52224
	ds_read_b128 v[234:237], v162 offset:53248
	ds_read_b128 v[238:241], v162 offset:54272
	ds_read_b128 v[242:245], v162 offset:55296
	ds_read_b128 v[246:249], v162 offset:56320
	global_load_lds_dwordx4 v[158:159], off
	s_add_i32 m0, s24, 0x2000
	s_add_u32 s20, s20, 0x40080
	v_lshl_add_u64 v[158:159], v[176:177], 0, s[34:35]
	s_addc_u32 s21, s21, 0
	s_add_i32 s24, s50, s29
	global_load_lds_dwordx4 v[158:159], off
	v_lshl_add_u64 v[158:159], s[20:21], 0, v[134:135]
	s_mov_b32 m0, s24
	s_nop 0
	global_load_lds_dwordx4 v[158:159], off
	v_lshl_add_u64 v[158:159], s[20:21], 0, v[130:131]
	s_add_i32 m0, s24, 0x2000
	s_nop 0
	global_load_lds_dwordx4 v[158:159], off
	v_lshl_add_u64 v[158:159], v[250:251], 0, s[34:35]
	s_mov_b32 m0, s42
	s_nop 0
	global_load_lds_dwordx4 v[158:159], off
	v_lshl_add_u64 v[158:159], v[200:201], 0, s[34:35]
	s_mov_b32 m0, s43
	s_nop 0
	global_load_lds_dwordx4 v[158:159], off
	s_waitcnt vmcnt(8)
	s_waitcnt lgkmcnt(0)
	s_barrier
	s_setprio 1
	s_waitcnt lgkmcnt(0)
	v_mfma_f32_16x16x32_bf16 v[62:65], v[164:167], v[218:221], v[62:65]
	v_mfma_f32_16x16x32_bf16 v[58:61], v[172:175], v[218:221], v[58:61]
	v_mfma_f32_16x16x32_bf16 v[46:49], v[164:167], v[226:229], v[46:49]
	v_mfma_f32_16x16x32_bf16 v[42:45], v[172:175], v[226:229], v[42:45]
	v_mfma_f32_16x16x32_bf16 v[30:33], v[164:167], v[234:237], v[30:33]
	v_mfma_f32_16x16x32_bf16 v[26:29], v[172:175], v[234:237], v[26:29]
	v_mfma_f32_16x16x32_bf16 v[14:17], v[164:167], v[242:245], v[14:17]
	v_mfma_f32_16x16x32_bf16 v[10:13], v[172:175], v[242:245], v[10:13]
	v_mfma_f32_16x16x32_bf16 v[62:65], v[168:171], v[222:225], v[62:65]
	v_mfma_f32_16x16x32_bf16 v[58:61], v[180:183], v[222:225], v[58:61]
	v_mfma_f32_16x16x32_bf16 v[46:49], v[168:171], v[230:233], v[46:49]
	v_mfma_f32_16x16x32_bf16 v[42:45], v[180:183], v[230:233], v[42:45]
	v_mfma_f32_16x16x32_bf16 v[30:33], v[168:171], v[238:241], v[30:33]
	v_mfma_f32_16x16x32_bf16 v[26:29], v[180:183], v[238:241], v[26:29]
	v_mfma_f32_16x16x32_bf16 v[14:17], v[168:171], v[246:249], v[14:17]
	v_mfma_f32_16x16x32_bf16 v[10:13], v[180:183], v[246:249], v[10:13]
	s_setprio 0
	s_setprio 1
	v_mfma_f32_16x16x32_bf16 v[54:57], v[184:187], v[218:221], v[54:57]
	v_mfma_f32_16x16x32_bf16 v[50:53], v[210:213], v[218:221], v[50:53]
	v_mfma_f32_16x16x32_bf16 v[38:41], v[184:187], v[226:229], v[38:41]
	v_mfma_f32_16x16x32_bf16 v[34:37], v[210:213], v[226:229], v[34:37]
	v_mfma_f32_16x16x32_bf16 v[22:25], v[184:187], v[234:237], v[22:25]
	v_mfma_f32_16x16x32_bf16 v[18:21], v[210:213], v[234:237], v[18:21]
	v_mfma_f32_16x16x32_bf16 v[6:9], v[184:187], v[242:245], v[6:9]
	v_mfma_f32_16x16x32_bf16 v[2:5], v[210:213], v[242:245], v[2:5]
	v_mfma_f32_16x16x32_bf16 v[54:57], v[188:191], v[222:225], v[54:57]
	v_mfma_f32_16x16x32_bf16 v[50:53], v[214:217], v[222:225], v[50:53]
	v_mfma_f32_16x16x32_bf16 v[38:41], v[188:191], v[230:233], v[38:41]
	v_mfma_f32_16x16x32_bf16 v[34:37], v[214:217], v[230:233], v[34:37]
	v_mfma_f32_16x16x32_bf16 v[22:25], v[188:191], v[238:241], v[22:25]
	v_mfma_f32_16x16x32_bf16 v[18:21], v[214:217], v[238:241], v[18:21]
	v_mfma_f32_16x16x32_bf16 v[6:9], v[188:191], v[246:249], v[6:9]
	v_mfma_f32_16x16x32_bf16 v[2:5], v[214:217], v[246:249], v[2:5]
	s_setprio 0
	s_barrier
	s_add_i32 s48, s48, 2
	s_add_u32 s2, s2, 0x100
	s_addc_u32 s3, s3, 0
	s_cmp_gt_u32 s48, 13
	s_cbranch_scc0 .LBB0_230
	s_add_i32 s2, s22, s12
	s_branch .Lgt_epi
.Lgt_tail:
	s_waitcnt vmcnt(0)
	s_cmpk_gt_u32 s27, 0xff
	s_cbranch_scc1 .LBB0_234
	s_barrier
